# dil KV loop: the 8 K-fragment ds_read_b128 hoisted to right after the barrier (under a scalar skip test) so the next-tile address math and global loads overlap the LDS latency
# baseline (speedup 1.0000x reference)
; #define LAS __attribute__((address_space(3)))
; template <int MODE, class SF> ...
;     ...
;     for (int s = 0; s < 4; ++s) { ka[s] = *(LAS const bf16x8*)(ksb + r * KSB + (16 * s + 8 * hh) * 2); kb2[s] = *(LAS const bf16x8*)(ksb + (32 + r) * KSB + (16 * s + 8 * hh) * 2); }
.LBB0_863:
	s_waitcnt vmcnt(1)
	v_and_b32_e32 v53, 0xffff0000, v5
	v_and_b32_e32 v51, 0xffff0000, v4
	v_lshlrev_b32_e32 v52, 16, v5
	v_lshlrev_b32_e32 v50, 16, v4
	v_pk_mul_f32 v[48:49], v[50:51], v[50:51]
	v_and_b32_e32 v57, 0xffff0000, v2
	v_and_b32_e32 v55, 0xffff0000, v3
	v_lshlrev_b32_e32 v54, 16, v3
	v_lshlrev_b32_e32 v56, 16, v2
	v_pk_fma_f32 v[48:49], v[52:53], v[52:53], v[48:49]
	s_mul_i32 s0, s6, 0x2400
	s_mul_i32 s98, s6, 0x3000
	s_add_i32 s16, s0, 0
	v_pk_fma_f32 v[48:49], v[54:55], v[54:55], v[48:49]
	v_pk_fma_f32 v[48:49], v[56:57], v[56:57], v[48:49]
	v_add_f32_e32 v48, v48, v49
	s_lshl_b32 s0, s6, 9
	s_sub_i32 s9, s16, s0
	s_cmp_ge_u32 s13, s24
	s_cselect_b64 s[4:5], -1, 0
	s_nop 1
	v_add_f32_dpp v48, v48, v48 quad_perm:[1,0,3,2] row_mask:0xf bank_mask:0xf
	s_nop 1
	v_add_f32_dpp v48, v48, v48 quad_perm:[2,3,0,1] row_mask:0xf bank_mask:0xf
	s_nop 1
	v_add_f32_dpp v48, v48, v48 row_half_mirror row_mask:0xf bank_mask:0xf
	v_fmamk_f32 v48, v48, 0x3c800000, v139
	v_rsq_f32_e32 v58, v48
	s_nop 0
	v_pk_mul_f32 v[48:49], v[58:59], v[56:57] op_sel_hi:[0,1]
	v_pk_mul_f32 v[54:55], v[58:59], v[54:55] op_sel_hi:[0,1]
	v_pk_mul_f32 v[50:51], v[58:59], v[50:51] op_sel_hi:[0,1]
	v_pk_mul_f32 v[52:53], v[58:59], v[52:53] op_sel_hi:[0,1]
	v_pk_mul_f32 v[48:49], v[14:15], v[48:49]
	v_pk_mul_f32 v[54:55], v[96:97], v[54:55]
	v_pk_mul_f32 v[50:51], v[98:99], v[50:51]
	v_pk_mul_f32 v[52:53], v[100:101], v[52:53]
	v_cvt_pk_bf16_f32 v48, v48, v49
	v_cvt_pk_bf16_f32 v49, v54, v55
	v_cvt_pk_bf16_f32 v50, v50, v51
	v_cvt_pk_bf16_f32 v51, v52, v53
	v_add3_u32 v52, s16, v95, v108
	ds_write_b128 v52, v[48:51]
	v_add_u32_e32 v48, s98, v110
	s_and_b64 vcc, exec, s[4:5]
	s_waitcnt vmcnt(0)
	ds_write_b128 v48, v[6:9] offset:18432
	s_waitcnt lgkmcnt(0)
	s_barrier
	s_add_i32 s0, s43, 63
	s_cmp_lt_i32 s0, s7
	s_cselect_b64 s[0:1], -1, 0
	s_cmp_gt_i32 s43, s8
	s_cselect_b64 s[26:27], -1, 0
	s_or_b64 s[100:101], s[0:1], s[26:27]
	s_cmp_lg_u64 s[100:101], 0
	s_cbranch_scc1 .Ldil_noK
	v_add3_u32 v56, s16, v111, v0
	ds_read_b128 v[48:51], v56
	ds_read_b128 v[116:119], v56 offset:32
	ds_read_b128 v[52:55], v56 offset:4608
	ds_read_b128 v[120:123], v56 offset:4640
	ds_read_b128 v[190:193], v56 offset:64
	ds_read_b128 v[194:197], v56 offset:96
	ds_read_b128 v[198:201], v56 offset:4672
	ds_read_b128 v[202:205], v56 offset:4704
.Ldil_noK:
	s_cbranch_vccnz .LBB0_867
	v_add_u32_e32 v185, s43, v114
	v_cmp_lt_i32_e32 vcc, -1, v185
	v_cmp_gt_i32_e64 s[0:1], s30, v185
	s_and_b64 s[26:27], vcc, s[0:1]
	v_mov_b32_e32 v9, 0
	v_mov_b32_e32 v5, 0
	v_mov_b32_e32 v4, 0
	v_mov_b32_e32 v3, 0
	v_mov_b32_e32 v2, 0
	v_mov_b32_e32 v8, 0
	v_mov_b32_e32 v7, 0
	v_mov_b32_e32 v6, 0
	s_and_saveexec_b64 s[0:1], s[26:27]
	s_cbranch_execz .LBB0_866
	v_mad_u64_u32 v[2:3], s[26:27], s44, v185, 0
	v_lshlrev_b64 v[2:3], 1, v[2:3]
	v_lshl_add_u64 v[4:5], v[102:103], 0, v[2:3]
	v_lshl_add_u64 v[6:7], v[104:105], 0, v[2:3]
	global_load_dwordx4 v[2:5], v[4:5], off
	s_nop 0
	global_load_dwordx4 v[6:9], v[6:7], off

; #define LAS __attribute__((address_space(3)))
; #define MFMA32(a, b, c) __builtin_amdgcn_mfma_f32_32x32x16_bf16((a), (b), (c), 0, 0, 0)
; __device__ __forceinline__ int crow(int i, int h) { return (i & 3) + 8 * (i >> 2) + 4 * h; }
; template <int MODE, class SF> ...
;     ...
; #pragma unroll
;     for (int s = 0; s < 4; ++s) { ka[s] = *(LAS const bf16x8*)(ksb + r * KSB + (16 * s + 8 * hh) * 2); kb2[s] = *(LAS const bf16x8*)(ksb + (32 + r) * KSB + (16 * s + 8 * hh) * 2); }
;     __builtin_amdgcn_s_setprio(1);
; #pragma unroll
;     for (int s = 0; s < 4; ++s) { s0 = MFMA32(ka[s], qf[s], s0); s1 = MFMA32(kb2[s], qf[s], s1); }
;     __builtin_amdgcn_s_setprio(0);
;     __builtin_amdgcn_sched_barrier(0);
; #pragma unroll
;     for (int i = 0; i < 16; ++i) { s0[i] = sf(s0[i], crow(i, hh)); s1[i] = sf(s1[i], 32 + crow(i, hh)); }
.LBB0_867:
	s_add_i32 s0, s43, 63
	s_cmp_lt_i32 s0, s7
	s_cselect_b64 s[0:1], -1, 0
	s_cmp_gt_i32 s43, s8
	s_cselect_b64 s[26:27], -1, 0
	s_or_b64 s[0:1], s[0:1], s[26:27]
	s_and_b64 vcc, exec, s[0:1]
	s_cbranch_vccnz .LBB0_871
	s_setprio 1
	s_waitcnt lgkmcnt(7)
	v_mfma_f32_32x32x16_bf16 v[64:79], v[48:51], v[88:91], 0
	s_waitcnt lgkmcnt(5)
	v_mfma_f32_32x32x16_bf16 v[48:63], v[52:55], v[88:91], 0
	v_mfma_f32_32x32x16_bf16 v[64:79], v[116:119], v[84:87], v[64:79]
	s_waitcnt lgkmcnt(4)
	v_mfma_f32_32x32x16_bf16 v[48:63], v[120:123], v[84:87], v[48:63]
	s_waitcnt lgkmcnt(3)
	v_mfma_f32_32x32x16_bf16 v[64:79], v[190:193], v[80:83], v[64:79]
	s_waitcnt lgkmcnt(1)
	v_mfma_f32_32x32x16_bf16 v[48:63], v[198:201], v[80:83], v[48:63]
	v_mfma_f32_32x32x16_bf16 v[64:79], v[194:197], v[10:13], v[64:79]
	s_waitcnt lgkmcnt(0)
	v_mfma_f32_32x32x16_bf16 v[48:63], v[202:205], v[10:13], v[48:63]
	s_setprio 0
	v_add_u32_e32 v190, s98, v112
	ds_read_b64_tr_b16 v[194:195], v190 offset:18432
	ds_read_b64_tr_b16 v[196:197], v190 offset:19968
	ds_read_b64_tr_b16 v[198:199], v190 offset:18496
	ds_read_b64_tr_b16 v[200:201], v190 offset:20032
	ds_read_b64_tr_b16 v[202:203], v190 offset:21504
	ds_read_b64_tr_b16 v[204:205], v190 offset:23040
	v_add_u32_e32 v116, 27, v113
	v_cvt_f32_u32_e32 v117, v116
	v_add_u32_e32 v118, -5, v113
	v_cvt_f32_u32_e32 v119, v118
	v_cmp_gt_u32_e32 vcc, s33, v116
	s_nop 3
	v_fma_f32 v64, -v93, v117, v64
	v_add_u32_e32 v116, 26, v113
	v_cndmask_b32_e32 v64, v215, v64, vcc
	v_cvt_f32_u32_e32 v117, v116
	v_cmp_gt_u32_e32 vcc, s33, v118
	v_add_u32_e32 v118, -6, v113
	v_fma_f32 v48, -v93, v119, v48
	v_cvt_f32_u32_e32 v119, v118
	v_cndmask_b32_e32 v48, v215, v48, vcc
	v_fma_f32 v65, -v93, v117, v65
	v_cmp_gt_u32_e32 vcc, s33, v116
	v_fma_f32 v49, -v93, v119, v49
	v_add_u32_e32 v116, 25, v113
	v_cndmask_b32_e32 v65, v215, v65, vcc
	v_cmp_gt_u32_e32 vcc, s33, v118
	v_cvt_f32_u32_e32 v117, v116
	v_fma_f32 v66, -v93, v117, v66
	v_cndmask_b32_e32 v118, v215, v49, vcc
	v_add_u32_e32 v49, -7, v113
	v_cvt_f32_u32_e32 v119, v49
	v_cmp_gt_u32_e32 vcc, s33, v116
	v_add_u32_e32 v116, 24, v113
	v_cvt_f32_u32_e32 v117, v116
	v_cndmask_b32_e32 v66, v215, v66, vcc
	v_fma_f32 v50, -v93, v119, v50
	v_cmp_gt_u32_e32 vcc, s33, v49
	v_add_u32_e32 v49, -8, v113
	v_fma_f32 v67, -v93, v117, v67
	v_cndmask_b32_e32 v119, v215, v50, vcc
	v_cvt_f32_u32_e32 v50, v49
	v_cmp_gt_u32_e32 vcc, s33, v116
	v_fma_f32 v50, -v93, v50, v51
	v_add_u32_e32 v51, 19, v113
	v_cndmask_b32_e32 v67, v215, v67, vcc
	v_cvt_f32_u32_e32 v116, v51
	v_cmp_gt_u32_e32 vcc, s33, v49
	v_add_u32_e32 v49, -13, v113
	v_fma_f32 v68, -v93, v116, v68
	v_cndmask_b32_e32 v117, v215, v50, vcc
	v_cvt_f32_u32_e32 v50, v49
	v_cmp_gt_u32_e32 vcc, s33, v51
	v_add_u32_e32 v51, 18, v113
	v_fma_f32 v50, -v93, v50, v52
	v_cndmask_b32_e32 v116, v215, v68, vcc
	v_cvt_f32_u32_e32 v52, v51
	v_cmp_gt_u32_e32 vcc, s33, v49
	v_add_u32_e32 v49, -14, v113
	v_fma_f32 v52, -v93, v52, v69
	v_cndmask_b32_e32 v120, v215, v50, vcc
	v_cvt_f32_u32_e32 v50, v49
	v_cmp_gt_u32_e32 vcc, s33, v51
	v_add_u32_e32 v51, 17, v113
	v_fma_f32 v50, -v93, v50, v53
	v_cndmask_b32_e32 v69, v215, v52, vcc
	v_cvt_f32_u32_e32 v52, v51
	v_cmp_gt_u32_e32 vcc, s33, v49
	v_add_u32_e32 v49, -15, v113
	v_fma_f32 v52, -v93, v52, v70
	v_cndmask_b32_e32 v121, v215, v50, vcc
	v_cvt_f32_u32_e32 v50, v49
	v_cmp_gt_u32_e32 vcc, s33, v51
	v_add_u32_e32 v51, 16, v113
	v_fma_f32 v50, -v93, v50, v54
	v_cndmask_b32_e32 v122, v215, v52, vcc
	v_cvt_f32_u32_e32 v52, v51
	v_cmp_gt_u32_e32 vcc, s33, v49
	v_add_u32_e32 v49, -16, v113
	v_fma_f32 v52, -v93, v52, v71
	v_cndmask_b32_e32 v123, v215, v50, vcc
	v_cvt_f32_u32_e32 v50, v49
	v_cmp_gt_u32_e32 vcc, s33, v51
	v_add_u32_e32 v51, 11, v113
	v_fma_f32 v50, -v93, v50, v55
	v_cndmask_b32_e32 v71, v215, v52, vcc
	v_cvt_f32_u32_e32 v52, v51
	v_cmp_gt_u32_e32 vcc, s33, v49
	v_subrev_u32_e32 v49, 21, v113
	v_fma_f32 v52, -v93, v52, v72
	v_cndmask_b32_e32 v55, v215, v50, vcc
	v_cvt_f32_u32_e32 v50, v49
	v_cmp_gt_u32_e32 vcc, s33, v51
	v_add_u32_e32 v51, 10, v113
	v_fma_f32 v50, -v93, v50, v56
	v_cndmask_b32_e32 v140, v215, v52, vcc
	v_cvt_f32_u32_e32 v52, v51
	v_cmp_gt_u32_e32 vcc, s33, v49
	v_subrev_u32_e32 v49, 22, v113
	v_fma_f32 v52, -v93, v52, v73
	v_cndmask_b32_e32 v141, v215, v50, vcc
	v_cvt_f32_u32_e32 v50, v49
	v_cmp_gt_u32_e32 vcc, s33, v51
	v_add_u32_e32 v51, 9, v113
	v_fma_f32 v50, -v93, v50, v57
	v_cndmask_b32_e32 v73, v215, v52, vcc
	v_cvt_f32_u32_e32 v52, v51
	v_cmp_gt_u32_e32 vcc, s33, v49
	v_subrev_u32_e32 v49, 23, v113
	v_fma_f32 v52, -v93, v52, v74
	v_cndmask_b32_e32 v57, v215, v50, vcc
	v_cvt_f32_u32_e32 v50, v49
	v_cmp_gt_u32_e32 vcc, s33, v51
	v_add_u32_e32 v51, 8, v113
	v_fma_f32 v50, -v93, v50, v58
	v_cndmask_b32_e32 v146, v215, v52, vcc
	v_cvt_f32_u32_e32 v52, v51
	v_cmp_gt_u32_e32 vcc, s33, v49
	v_subrev_u32_e32 v49, 24, v113
	v_fma_f32 v52, -v93, v52, v75
	v_cndmask_b32_e32 v147, v215, v50, vcc
	v_cvt_f32_u32_e32 v50, v49
	v_cmp_gt_u32_e32 vcc, s33, v51
	v_add_u32_e32 v51, 3, v113
	v_fma_f32 v50, -v93, v50, v59
	v_cndmask_b32_e32 v165, v215, v52, vcc
	v_cvt_f32_u32_e32 v52, v51
	v_cmp_gt_u32_e32 vcc, s33, v49
	v_subrev_u32_e32 v49, 29, v113
	v_fma_f32 v52, -v93, v52, v76
	v_cndmask_b32_e32 v167, v215, v50, vcc
	v_cvt_f32_u32_e32 v50, v49
	v_cmp_gt_u32_e32 vcc, s33, v51
	v_add_u32_e32 v51, 2, v113
	v_fma_f32 v50, -v93, v50, v60
	v_cndmask_b32_e32 v169, v215, v52, vcc
	v_cvt_f32_u32_e32 v52, v51
	v_cmp_gt_u32_e32 vcc, s33, v49
	v_subrev_u32_e32 v49, 30, v113
	v_fma_f32 v52, -v93, v52, v77
	v_cndmask_b32_e32 v171, v215, v50, vcc
; __device__ __forceinline__ float sum32(float v) { auto rr = __builtin_amdgcn_permlane32_swap(__float_as_uint(v), __float_as_uint(v), false, false); return __uint_as_float(rr[0]) + __uint_as_float(rr[1]); }
; __device__ __forceinline__ float max32(float v) { auto rr = __builtin_amdgcn_permlane32_swap(__float_as_uint(v), __float_as_uint(v), false, false); return fmaxf(__uint_as_float(rr[0]), __uint_as_float(rr[1])); }
; #define EXP2(x) __builtin_amdgcn_exp2f(x)
; template <int MODE, class SF> ...
;     ...
;     if (MODE != 2) {
;         float mloc = fmaxf(s0[0], s1[0]);
; #pragma unroll
;         for (int i = 1; i < 16; ++i) mloc = fmaxf(mloc, fmaxf(s0[i], s1[i]));
;         mloc = max32(mloc);
;         const float mnew = fmaxf(m, mloc), msafe = mnew == -INFINITY ? 0.f : mnew, corr = EXP2(m - msafe);
;         float psum = 0.f;
; #pragma unroll
;         for (int i = 0; i < 16; ++i) { s0[i] = EXP2(s0[i] - msafe); s1[i] = EXP2(s1[i] - msafe); psum += s0[i] + s1[i]; }
;         psum = sum32(psum);
;         l = l * corr + psum; m = mnew;
;         if (MODE == 0 && !__all(corr == 1.f)) {
; #pragma unroll
;             for (int i = 0; i < 16; ++i) { o0[i] *= corr; o1[i] *= corr; } }
	v_cvt_f32_u32_e32 v50, v49
	v_cmp_gt_u32_e32 vcc, s33, v51
	v_add_u32_e32 v51, 1, v113
	v_fma_f32 v50, -v93, v50, v61
	v_cndmask_b32_e32 v173, v215, v52, vcc
	v_cvt_f32_u32_e32 v52, v51
	v_cmp_gt_u32_e32 vcc, s33, v49
	v_subrev_u32_e32 v49, 31, v113
	v_fma_f32 v52, -v93, v52, v78
	v_cndmask_b32_e32 v175, v215, v50, vcc
	v_cvt_f32_u32_e32 v50, v49
	v_cmp_gt_u32_e32 vcc, s33, v51
	v_cvt_f32_u32_e32 v51, v113
	v_fma_f32 v50, -v93, v50, v62
	v_cndmask_b32_e32 v177, v215, v52, vcc
	v_cmp_gt_u32_e32 vcc, s33, v49
	v_subrev_u32_e32 v49, 32, v113
	v_fma_f32 v51, -v93, v51, v79
	v_cndmask_b32_e32 v179, v215, v50, vcc
	v_cvt_f32_u32_e32 v50, v49
	v_cmp_gt_u32_e32 vcc, s33, v113
	v_fma_f32 v50, -v93, v50, v63
	s_nop 0
	v_cndmask_b32_e32 v181, v215, v51, vcc
	v_cmp_gt_u32_e32 vcc, s33, v49
	v_max_f32_e32 v49, v65, v118
	v_max3_f32 v49, v64, v48, v49
	v_cndmask_b32_e32 v183, v215, v50, vcc
	v_max_f32_e32 v50, v66, v119
	v_max_f32_e32 v51, v67, v117
	v_max3_f32 v49, v49, v50, v51
	v_max_f32_e32 v50, v116, v120
	v_max_f32_e32 v51, v69, v121
	v_max3_f32 v49, v49, v50, v51
	v_max_f32_e32 v50, v122, v123
	v_max_f32_e32 v51, v71, v55
	v_max3_f32 v49, v49, v50, v51
	v_max_f32_e32 v50, v140, v141
	v_max_f32_e32 v51, v73, v57
	v_max3_f32 v49, v49, v50, v51
	v_max_f32_e32 v50, v146, v147
	v_max_f32_e32 v51, v165, v167
	v_max3_f32 v49, v49, v50, v51
	v_max_f32_e32 v50, v169, v171
	v_max_f32_e32 v51, v173, v175
	v_max3_f32 v49, v49, v50, v51
	v_max_f32_e32 v50, v177, v179
	v_max_f32_e32 v51, v181, v183
	v_max3_f32 v49, v49, v50, v51
	v_mov_b32_e32 v50, v49
	s_nop 1
	v_permlane32_swap_b32_e32 v49, v50
	v_max3_f32 v49, v115, v49, v50
	v_cmp_neq_f32_e32 vcc, s34, v49
	s_nop 1
	v_cndmask_b32_e32 v185, 0, v49, vcc
	v_sub_f32_e32 v50, v64, v185
	v_sub_f32_e32 v48, v48, v185
	v_exp_f32_e32 v62, v50
	v_exp_f32_e32 v50, v48
	v_sub_f32_e32 v48, v65, v185
	v_exp_f32_e32 v64, v48
	v_sub_f32_e32 v48, v118, v185
	v_add_f32_e32 v52, v62, v50
	v_add_f32_e32 v54, 0, v52
	v_sub_f32_e32 v52, v66, v185
	v_exp_f32_e32 v51, v48
	v_exp_f32_e32 v66, v52
	v_sub_f32_e32 v52, v119, v185
	v_exp_f32_e32 v52, v52
	v_add_f32_e32 v56, v64, v51
	v_sub_f32_e32 v53, v67, v185
	v_add_f32_e32 v54, v56, v54
	v_add_f32_e32 v56, v66, v52
	v_exp_f32_e32 v68, v53
	v_sub_f32_e32 v53, v117, v185
	v_add_f32_e32 v58, v56, v54
	v_sub_f32_e32 v54, v116, v185
	v_exp_f32_e32 v53, v53
	v_exp_f32_e32 v70, v54
	v_sub_f32_e32 v54, v120, v185
	v_exp_f32_e32 v54, v54
	v_add_f32_e32 v59, v68, v53
	v_sub_f32_e32 v56, v69, v185
	v_add_f32_e32 v58, v59, v58
	v_add_f32_e32 v59, v70, v54
	v_exp_f32_e32 v72, v56
	v_sub_f32_e32 v56, v121, v185
	v_add_f32_e32 v59, v59, v58
	v_sub_f32_e32 v58, v122, v185
	v_exp_f32_e32 v56, v56
	v_exp_f32_e32 v74, v58
	v_sub_f32_e32 v58, v123, v185
	v_exp_f32_e32 v58, v58
	v_add_f32_e32 v61, v72, v56
	v_sub_f32_e32 v60, v71, v185
	v_sub_f32_e32 v55, v55, v185
	v_exp_f32_e32 v76, v60
	v_exp_f32_e32 v60, v55
	v_add_f32_e32 v55, v61, v59
	v_add_f32_e32 v59, v74, v58
	v_add_f32_e32 v59, v59, v55
	v_sub_f32_e32 v55, v140, v185
	v_exp_f32_e32 v71, v55
	v_sub_f32_e32 v55, v141, v185
	v_exp_f32_e32 v55, v55
	v_add_f32_e32 v61, v76, v60
	v_sub_f32_e32 v63, v73, v185
	v_add_f32_e32 v59, v61, v59
	v_add_f32_e32 v61, v71, v55
	v_exp_f32_e32 v73, v63
	v_sub_f32_e32 v57, v57, v185
	v_add_f32_e32 v63, v61, v59
	v_sub_f32_e32 v59, v146, v185
	v_exp_f32_e32 v57, v57
	v_exp_f32_e32 v75, v59
	v_sub_f32_e32 v59, v147, v185
	v_exp_f32_e32 v59, v59
	v_add_f32_e32 v65, v73, v57
	v_sub_f32_e32 v61, v165, v185
	v_add_f32_e32 v63, v65, v63
	v_add_f32_e32 v65, v75, v59
	v_exp_f32_e32 v77, v61
	v_sub_f32_e32 v61, v167, v185
	v_add_f32_e32 v67, v65, v63
	v_sub_f32_e32 v63, v169, v185
	v_exp_f32_e32 v61, v61
	v_exp_f32_e32 v78, v63
	v_sub_f32_e32 v63, v171, v185
	v_sub_f32_e32 v65, v173, v185
	v_exp_f32_e32 v63, v63
	v_exp_f32_e32 v79, v65
	v_sub_f32_e32 v65, v175, v185
	v_exp_f32_e32 v65, v65
	v_add_f32_e32 v69, v77, v61
	v_add_f32_e32 v67, v69, v67
	v_add_f32_e32 v69, v78, v63
	v_add_f32_e32 v67, v69, v67
	v_add_f32_e32 v69, v79, v65
	v_add_f32_e32 v117, v69, v67
	v_sub_f32_e32 v67, v177, v185
	v_sub_f32_e32 v48, v115, v185
	v_exp_f32_e32 v115, v67
	v_sub_f32_e32 v67, v179, v185
	v_sub_f32_e32 v69, v181, v185
	v_exp_f32_e32 v67, v67
	v_exp_f32_e32 v116, v69
	v_sub_f32_e32 v69, v183, v185
	v_exp_f32_e32 v69, v69
	v_exp_f32_e32 v48, v48
	v_add_f32_e32 v118, v115, v67
	v_add_f32_e32 v117, v118, v117
	v_add_f32_e32 v118, v116, v69
	v_add_f32_e32 v117, v118, v117
	v_mov_b32_e32 v118, v117
	v_cmp_eq_f32_e32 vcc, 1.0, v48
	s_cmp_eq_u64 vcc, exec
	v_permlane32_swap_b32_e32 v117, v118
	s_cbranch_scc1 .LBB0_870
	v_pk_mul_f32 v[30:31], v[30:31], v[48:49] op_sel_hi:[1,0]
	v_pk_mul_f32 v[28:29], v[28:29], v[48:49] op_sel_hi:[1,0]
	v_pk_mul_f32 v[26:27], v[26:27], v[48:49] op_sel_hi:[1,0]
	v_pk_mul_f32 v[24:25], v[24:25], v[48:49] op_sel_hi:[1,0]
	v_pk_mul_f32 v[22:23], v[22:23], v[48:49] op_sel_hi:[1,0]
	v_pk_mul_f32 v[20:21], v[20:21], v[48:49] op_sel_hi:[1,0]
	v_pk_mul_f32 v[18:19], v[18:19], v[48:49] op_sel_hi:[1,0]
	v_pk_mul_f32 v[16:17], v[16:17], v[48:49] op_sel_hi:[1,0]
	v_pk_mul_f32 v[46:47], v[46:47], v[48:49] op_sel_hi:[1,0]
	v_pk_mul_f32 v[44:45], v[44:45], v[48:49] op_sel_hi:[1,0]
	v_pk_mul_f32 v[42:43], v[42:43], v[48:49] op_sel_hi:[1,0]
	v_pk_mul_f32 v[40:41], v[40:41], v[48:49] op_sel_hi:[1,0]
	v_pk_mul_f32 v[38:39], v[38:39], v[48:49] op_sel_hi:[1,0]
	v_pk_mul_f32 v[36:37], v[36:37], v[48:49] op_sel_hi:[1,0]
	v_pk_mul_f32 v[34:35], v[34:35], v[48:49] op_sel_hi:[1,0]
	v_pk_mul_f32 v[32:33], v[32:33], v[48:49] op_sel_hi:[1,0]
